# K-loop load segments: m0 written one instruction earlier, s_nop pads removed
# speedup vs baseline: 1.0044x; 1.0021x over previous
; #define PG8_STAGE(bufoff, gbase, voff) do { _Pragma("unroll") for (int _i = 0; _i < 2; ++_i) \
;         __builtin_amdgcn_global_load_lds((const unsigned*)((const char*)(gbase) + (voff)[_i]), (PG8_LAS unsigned*)(lds + (bufoff) + ldsw + _i * 8192), 16, 0, 0); } while (0)
; #define PG8_LDA(dst, b, h) do { _Pragma("unroll") for (int m = 0; m < 4; ++m) _Pragma("unroll") for (int k = 0; k < 2; ++k) dst[m][k] = *(const PG8_LAS bf16x8*)(lds + PG8_SA(b, h) + aoff + m * 2048 + k * 1024); } while (0)
; #define PG8_LDB(dst, b, h) do { _Pragma("unroll") for (int n = 0; n < 2; ++n) _Pragma("unroll") for (int k = 0; k < 2; ++k) dst[n][k] = *(const PG8_LAS bf16x8*)(lds + PG8_SB(b, h) + boff + n * 2048 + k * 1024); } while (0)
; #define PG8_MMA(ai, bj, At, Bt) do { __builtin_amdgcn_s_setprio(1); _Pragma("unroll") for (int m = 0; m < 4; ++m) _Pragma("unroll") for (int n = 0; n < 2; ++n) _Pragma("unroll") for (int k = 0; k < 2; ++k) \
;         acc[ai][bj][m][n] = __builtin_amdgcn_mfma_f32_16x16x32_bf16(Bt[n][k], At[m][k], acc[ai][bj][m][n], 0, 0, 0); __builtin_amdgcn_s_setprio(0); } while (0)
; #define PG8_WAIT_V(n) asm volatile("s_waitcnt vmcnt(" #n ")" ::: "memory")
; #define PG8_WAIT_L(n) asm volatile("s_waitcnt lgkmcnt(" #n ")" ::: "memory")
; #define PG8_BAR __builtin_amdgcn_s_barrier()
; #define PG8_SCHED __builtin_amdgcn_sched_barrier(0)
; template <class Epi, class Sched, bool ALIGN_EPI = false, bool SP2 = false>
; __device__ __forceinline__ void gemm_phase(PG8_LAS unsigned char* lds, const Gemm g, const Sched& S, const Epi& E) {
;     ...
;             const bool last = (t == nt - 2);
;             const char* a1 = cA + (size_t)(t + 1) * kstep;
;             const char* a2 = last ? nA : cA + (size_t)(t + 2) * kstep; const char* b2 = last ? nB : cB + (size_t)(t + 2) * kstep;
;             const char* a3 = a2 + kstep; const char* b3 = b2 + kstep;
;             if (last && has_next) S.a_ready(nxt);
;             if constexpr (SP2) {
;             PG8_LDB(B0, 0, 0); PG8_LDB(B1, 0, 1); PG8_SCHED; PG8_LDA(At, 0, 0); PG8_STAGE(PG8_SA(1, 1), a1 + hstep, voffA);
;             PG8_WAIT_V(8); PG8_WAIT_L(0); PG8_BAR; PG8_MMA(0, 0, At, B0); PG8_MMA(0, 1, At, B1); PG8_BAR; PG8_SCHED;
;             PG8_LDA(At, 0, 1); PG8_STAGE(PG8_SB(0, 0), b2, voffB); PG8_STAGE(PG8_SB(0, 1), b2 + hstep, voffB); PG8_STAGE(PG8_SA(0, 0), a2, voffA);
.LBB0_441:
	s_add_i32 s66, 0, 0x10000
	s_add_i32 s67, 0, 0x14000
	v_add_u32_e32 v142, s66, v228
	v_add_u32_e32 v158, s67, v228
	ds_read_b128 v[130:133], v142
	ds_read_b128 v[134:137], v142 offset:1024
	ds_read_b128 v[138:141], v142 offset:2048
	ds_read_b128 v[142:145], v142 offset:3072
	ds_read_b128 v[146:149], v158
	ds_read_b128 v[150:153], v158 offset:1024
	ds_read_b128 v[154:157], v158 offset:2048
	ds_read_b128 v[158:161], v158 offset:3072
	v_lshl_add_u64 v[206:207], s[42:43], 0, v[190:191]
	s_add_i32 m0, s93, 0xc000
	ds_read_b128 v[162:165], v230
	ds_read_b128 v[166:169], v230 offset:1024
	ds_read_b128 v[170:173], v230 offset:2048
	ds_read_b128 v[174:177], v230 offset:3072
	ds_read_b128 v[178:181], v230 offset:4096
	ds_read_b128 v[194:197], v230 offset:5120
	ds_read_b128 v[198:201], v230 offset:6144
	ds_read_b128 v[202:205], v230 offset:7168
	s_add_i32 s61, s44, 2
	s_add_u32 s64, s42, 0x80
	s_addc_u32 s45, s43, 0
	s_cmp_eq_u32 s99, s44
	s_cselect_b32 s45, s29, s45
	s_cselect_b32 s44, s28, s64
	s_cselect_b32 s65, s21, s60
	s_cselect_b32 s64, s20, s17
	global_load_lds_dwordx4 v[206:207], off
	s_add_i32 m0, s93, 0xe000
	v_lshl_add_u64 v[206:207], s[42:43], 0, v[192:193]
	global_load_lds_dwordx4 v[206:207], off
	s_setprio 1
	s_waitcnt vmcnt(8) lgkmcnt(0)
	s_barrier
	v_mfma_f32_16x16x32_bf16 v[126:129], v[130:133], v[162:165], v[126:129]
	v_mfma_f32_16x16x32_bf16 v[122:125], v[138:141], v[162:165], v[122:125]
	v_mfma_f32_16x16x32_bf16 v[110:113], v[130:133], v[170:173], v[110:113]
	v_mfma_f32_16x16x32_bf16 v[102:105], v[138:141], v[170:173], v[102:105]
	v_mfma_f32_16x16x32_bf16 v[94:97], v[130:133], v[178:181], v[94:97]
	v_mfma_f32_16x16x32_bf16 v[86:89], v[138:141], v[178:181], v[86:89]
	v_mfma_f32_16x16x32_bf16 v[78:81], v[130:133], v[198:201], v[78:81]
	v_mfma_f32_16x16x32_bf16 v[70:73], v[138:141], v[198:201], v[70:73]
	v_mfma_f32_16x16x32_bf16 v[126:129], v[134:137], v[166:169], v[126:129]
	v_mfma_f32_16x16x32_bf16 v[122:125], v[142:145], v[166:169], v[122:125]
	v_mfma_f32_16x16x32_bf16 v[110:113], v[134:137], v[174:177], v[110:113]
	v_mfma_f32_16x16x32_bf16 v[102:105], v[142:145], v[174:177], v[102:105]
	v_mfma_f32_16x16x32_bf16 v[94:97], v[134:137], v[194:197], v[94:97]
	v_mfma_f32_16x16x32_bf16 v[86:89], v[142:145], v[194:197], v[86:89]
	v_mfma_f32_16x16x32_bf16 v[78:81], v[134:137], v[202:205], v[78:81]
	v_mfma_f32_16x16x32_bf16 v[70:73], v[142:145], v[202:205], v[70:73]
	v_mfma_f32_16x16x32_bf16 v[118:121], v[146:149], v[162:165], v[118:121]
	v_mfma_f32_16x16x32_bf16 v[114:117], v[154:157], v[162:165], v[114:117]
	v_mfma_f32_16x16x32_bf16 v[106:109], v[146:149], v[170:173], v[106:109]
	v_mfma_f32_16x16x32_bf16 v[98:101], v[154:157], v[170:173], v[98:101]
	v_mfma_f32_16x16x32_bf16 v[90:93], v[146:149], v[178:181], v[90:93]
	v_mfma_f32_16x16x32_bf16 v[82:85], v[154:157], v[178:181], v[82:85]
	v_mfma_f32_16x16x32_bf16 v[74:77], v[146:149], v[198:201], v[74:77]
	v_mfma_f32_16x16x32_bf16 v[66:69], v[154:157], v[198:201], v[66:69]
	v_mfma_f32_16x16x32_bf16 v[118:121], v[150:153], v[166:169], v[118:121]
	v_mfma_f32_16x16x32_bf16 v[114:117], v[158:161], v[166:169], v[114:117]
	v_mfma_f32_16x16x32_bf16 v[106:109], v[150:153], v[174:177], v[106:109]
	v_mfma_f32_16x16x32_bf16 v[98:101], v[158:161], v[174:177], v[98:101]
	v_mfma_f32_16x16x32_bf16 v[90:93], v[150:153], v[194:197], v[90:93]
	v_mfma_f32_16x16x32_bf16 v[82:85], v[158:161], v[194:197], v[82:85]
	v_mfma_f32_16x16x32_bf16 v[74:77], v[150:153], v[202:205], v[74:77]
	v_mfma_f32_16x16x32_bf16 v[66:69], v[158:161], v[202:205], v[66:69]
	s_barrier
	s_setprio 0
	ds_read_b128 v[162:165], v230 offset:16384
	ds_read_b128 v[166:169], v230 offset:17408
	ds_read_b128 v[170:173], v230 offset:18432
	ds_read_b128 v[174:177], v230 offset:19456
	ds_read_b128 v[178:181], v230 offset:20480
	ds_read_b128 v[194:197], v230 offset:21504
	ds_read_b128 v[198:201], v230 offset:22528
	ds_read_b128 v[202:205], v230 offset:23552
	s_add_i32 s66, s66, s92
	s_mov_b32 m0, s66
	v_lshl_add_u64 v[206:207], s[64:65], 0, v[184:185]
	global_load_lds_dwordx4 v[206:207], off
	s_add_i32 m0, s66, 0x2000
	v_lshl_add_u64 v[208:209], s[64:65], 0, v[188:189]
	s_add_u32 s64, s64, s26
	s_addc_u32 s65, s65, 0
	s_add_i32 s66, s67, s92
	global_load_lds_dwordx4 v[208:209], off
	v_lshl_add_u64 v[210:211], s[64:65], 0, v[184:185]
	s_mov_b32 m0, s66
	v_lshl_add_u64 v[232:233], s[64:65], 0, v[188:189]
	global_load_lds_dwordx4 v[210:211], off
	s_add_i32 m0, s66, 0x2000
	v_lshl_add_u64 v[234:235], s[44:45], 0, v[182:183]
	global_load_lds_dwordx4 v[232:233], off
	s_mov_b32 m0, s93
	v_lshl_add_u64 v[236:237], s[44:45], 0, v[186:187]
	global_load_lds_dwordx4 v[234:235], off
	s_mov_b32 m0, s94
	s_nop 0
	global_load_lds_dwordx4 v[236:237], off
	s_setprio 1
	s_waitcnt vmcnt(8) lgkmcnt(0)
	s_barrier
; #define PG8_STAGE(bufoff, gbase, voff) do { _Pragma("unroll") for (int _i = 0; _i < 2; ++_i) \
;         __builtin_amdgcn_global_load_lds((const unsigned*)((const char*)(gbase) + (voff)[_i]), (PG8_LAS unsigned*)(lds + (bufoff) + ldsw + _i * 8192), 16, 0, 0); } while (0)
; #define PG8_LDA(dst, b, h) do { _Pragma("unroll") for (int m = 0; m < 4; ++m) _Pragma("unroll") for (int k = 0; k < 2; ++k) dst[m][k] = *(const PG8_LAS bf16x8*)(lds + PG8_SA(b, h) + aoff + m * 2048 + k * 1024); } while (0)
; #define PG8_LDB(dst, b, h) do { _Pragma("unroll") for (int n = 0; n < 2; ++n) _Pragma("unroll") for (int k = 0; k < 2; ++k) dst[n][k] = *(const PG8_LAS bf16x8*)(lds + PG8_SB(b, h) + boff + n * 2048 + k * 1024); } while (0)
; #define PG8_MMA(ai, bj, At, Bt) do { __builtin_amdgcn_s_setprio(1); _Pragma("unroll") for (int m = 0; m < 4; ++m) _Pragma("unroll") for (int n = 0; n < 2; ++n) _Pragma("unroll") for (int k = 0; k < 2; ++k) \
;         acc[ai][bj][m][n] = __builtin_amdgcn_mfma_f32_16x16x32_bf16(Bt[n][k], At[m][k], acc[ai][bj][m][n], 0, 0, 0); __builtin_amdgcn_s_setprio(0); } while (0)
; #define PG8_WAIT_V(n) asm volatile("s_waitcnt vmcnt(" #n ")" ::: "memory")
; #define PG8_WAIT_L(n) asm volatile("s_waitcnt lgkmcnt(" #n ")" ::: "memory")
; #define PG8_BAR __builtin_amdgcn_s_barrier()
; #define PG8_SCHED __builtin_amdgcn_sched_barrier(0)
; template <class Epi, class Sched, bool ALIGN_EPI = false, bool SP2 = false>
; __device__ __forceinline__ void gemm_phase(PG8_LAS unsigned char* lds, const Gemm g, const Sched& S, const Epi& E) {
;     ...
;             PG8_WAIT_V(8); PG8_WAIT_L(0); PG8_BAR; PG8_MMA(1, 0, At, B0); PG8_MMA(1, 1, At, B1); PG8_BAR; PG8_SCHED;
;             PG8_LDB(B0, 1, 0); PG8_LDB(B1, 1, 1); PG8_SCHED; PG8_LDA(At, 1, 0); PG8_STAGE(PG8_SA(0, 1), a2 + hstep, voffA);
;             PG8_WAIT_V(8); PG8_WAIT_L(0); PG8_BAR; PG8_MMA(0, 0, At, B0); PG8_MMA(0, 1, At, B1); PG8_BAR; PG8_SCHED;
	v_mfma_f32_16x16x32_bf16 v[62:65], v[130:133], v[162:165], v[62:65]
	v_mfma_f32_16x16x32_bf16 v[54:57], v[138:141], v[162:165], v[54:57]
	v_mfma_f32_16x16x32_bf16 v[46:49], v[130:133], v[170:173], v[46:49]
	v_mfma_f32_16x16x32_bf16 v[38:41], v[138:141], v[170:173], v[38:41]
	v_mfma_f32_16x16x32_bf16 v[30:33], v[130:133], v[178:181], v[30:33]
	v_mfma_f32_16x16x32_bf16 v[22:25], v[138:141], v[178:181], v[22:25]
	v_mfma_f32_16x16x32_bf16 v[14:17], v[130:133], v[198:201], v[14:17]
	v_mfma_f32_16x16x32_bf16 v[6:9], v[138:141], v[198:201], v[6:9]
	v_mfma_f32_16x16x32_bf16 v[62:65], v[134:137], v[166:169], v[62:65]
	v_mfma_f32_16x16x32_bf16 v[54:57], v[142:145], v[166:169], v[54:57]
	v_mfma_f32_16x16x32_bf16 v[46:49], v[134:137], v[174:177], v[46:49]
	v_mfma_f32_16x16x32_bf16 v[38:41], v[142:145], v[174:177], v[38:41]
	v_mfma_f32_16x16x32_bf16 v[30:33], v[134:137], v[194:197], v[30:33]
	v_mfma_f32_16x16x32_bf16 v[22:25], v[142:145], v[194:197], v[22:25]
	v_mfma_f32_16x16x32_bf16 v[14:17], v[134:137], v[202:205], v[14:17]
	v_mfma_f32_16x16x32_bf16 v[6:9], v[142:145], v[202:205], v[6:9]
	v_mfma_f32_16x16x32_bf16 v[58:61], v[146:149], v[162:165], v[58:61]
	v_mfma_f32_16x16x32_bf16 v[50:53], v[154:157], v[162:165], v[50:53]
	v_mfma_f32_16x16x32_bf16 v[42:45], v[146:149], v[170:173], v[42:45]
	v_mfma_f32_16x16x32_bf16 v[34:37], v[154:157], v[170:173], v[34:37]
	v_mfma_f32_16x16x32_bf16 v[26:29], v[146:149], v[178:181], v[26:29]
	v_mfma_f32_16x16x32_bf16 v[18:21], v[154:157], v[178:181], v[18:21]
	v_mfma_f32_16x16x32_bf16 v[10:13], v[146:149], v[198:201], v[10:13]
	v_mfma_f32_16x16x32_bf16 v[2:5], v[154:157], v[198:201], v[2:5]
	v_mfma_f32_16x16x32_bf16 v[58:61], v[150:153], v[166:169], v[58:61]
	v_mfma_f32_16x16x32_bf16 v[50:53], v[158:161], v[166:169], v[50:53]
	v_mfma_f32_16x16x32_bf16 v[42:45], v[150:153], v[174:177], v[42:45]
	v_mfma_f32_16x16x32_bf16 v[34:37], v[158:161], v[174:177], v[34:37]
	v_mfma_f32_16x16x32_bf16 v[26:29], v[150:153], v[194:197], v[26:29]
	v_mfma_f32_16x16x32_bf16 v[18:21], v[158:161], v[194:197], v[18:21]
	v_mfma_f32_16x16x32_bf16 v[10:13], v[150:153], v[202:205], v[10:13]
	v_mfma_f32_16x16x32_bf16 v[2:5], v[158:161], v[202:205], v[2:5]
	s_barrier
	s_setprio 0
	ds_read_b128 v[162:165], v230 offset:32768
	ds_read_b128 v[166:169], v230 offset:33792
	ds_read_b128 v[170:173], v230 offset:34816
	ds_read_b128 v[174:177], v230 offset:35840
	ds_read_b128 v[178:181], v230 offset:36864
	ds_read_b128 v[194:197], v230 offset:37888
	ds_read_b128 v[198:201], v230 offset:38912
	ds_read_b128 v[202:205], v230 offset:39936
	s_add_i32 s64, 0, 0x18000
	s_add_i32 s65, 0, 0x1c000
	v_add_u32_e32 v142, s64, v228
	v_add_u32_e32 v158, s65, v228
	ds_read_b128 v[130:133], v142
	ds_read_b128 v[134:137], v142 offset:1024
	ds_read_b128 v[138:141], v142 offset:2048
	ds_read_b128 v[142:145], v142 offset:3072
	ds_read_b128 v[146:149], v158
	ds_read_b128 v[150:153], v158 offset:1024
	ds_read_b128 v[154:157], v158 offset:2048
	ds_read_b128 v[158:161], v158 offset:3072
	s_add_u32 s44, s44, s26
	s_addc_u32 s45, s45, 0
	s_mov_b32 m0, s95
	v_lshl_add_u64 v[238:239], s[44:45], 0, v[182:183]
	global_load_lds_dwordx4 v[238:239], off
	s_mov_b32 m0, s96
	v_lshl_add_u64 v[238:239], s[44:45], 0, v[186:187]
	global_load_lds_dwordx4 v[238:239], off
	s_setprio 1
	s_waitcnt vmcnt(8) lgkmcnt(0)
	s_barrier
	v_mfma_f32_16x16x32_bf16 v[126:129], v[130:133], v[162:165], v[126:129]
	v_mfma_f32_16x16x32_bf16 v[122:125], v[138:141], v[162:165], v[122:125]
	v_mfma_f32_16x16x32_bf16 v[110:113], v[130:133], v[170:173], v[110:113]
	v_mfma_f32_16x16x32_bf16 v[102:105], v[138:141], v[170:173], v[102:105]
	v_mfma_f32_16x16x32_bf16 v[94:97], v[130:133], v[178:181], v[94:97]
	v_mfma_f32_16x16x32_bf16 v[86:89], v[138:141], v[178:181], v[86:89]
	v_mfma_f32_16x16x32_bf16 v[78:81], v[130:133], v[198:201], v[78:81]
	v_mfma_f32_16x16x32_bf16 v[70:73], v[138:141], v[198:201], v[70:73]
	v_mfma_f32_16x16x32_bf16 v[126:129], v[134:137], v[166:169], v[126:129]
	v_mfma_f32_16x16x32_bf16 v[122:125], v[142:145], v[166:169], v[122:125]
	v_mfma_f32_16x16x32_bf16 v[110:113], v[134:137], v[174:177], v[110:113]
	v_mfma_f32_16x16x32_bf16 v[102:105], v[142:145], v[174:177], v[102:105]
	v_mfma_f32_16x16x32_bf16 v[94:97], v[134:137], v[194:197], v[94:97]
	v_mfma_f32_16x16x32_bf16 v[86:89], v[142:145], v[194:197], v[86:89]
	v_mfma_f32_16x16x32_bf16 v[78:81], v[134:137], v[202:205], v[78:81]
	v_mfma_f32_16x16x32_bf16 v[70:73], v[142:145], v[202:205], v[70:73]
	v_mfma_f32_16x16x32_bf16 v[118:121], v[146:149], v[162:165], v[118:121]
	v_mfma_f32_16x16x32_bf16 v[114:117], v[154:157], v[162:165], v[114:117]
	v_mfma_f32_16x16x32_bf16 v[106:109], v[146:149], v[170:173], v[106:109]
	v_mfma_f32_16x16x32_bf16 v[98:101], v[154:157], v[170:173], v[98:101]
	v_mfma_f32_16x16x32_bf16 v[90:93], v[146:149], v[178:181], v[90:93]
	v_mfma_f32_16x16x32_bf16 v[82:85], v[154:157], v[178:181], v[82:85]
	v_mfma_f32_16x16x32_bf16 v[74:77], v[146:149], v[198:201], v[74:77]
	v_mfma_f32_16x16x32_bf16 v[66:69], v[154:157], v[198:201], v[66:69]
	v_mfma_f32_16x16x32_bf16 v[118:121], v[150:153], v[166:169], v[118:121]
	v_mfma_f32_16x16x32_bf16 v[114:117], v[158:161], v[166:169], v[114:117]
	v_mfma_f32_16x16x32_bf16 v[106:109], v[150:153], v[174:177], v[106:109]
	v_mfma_f32_16x16x32_bf16 v[98:101], v[158:161], v[174:177], v[98:101]
	v_mfma_f32_16x16x32_bf16 v[90:93], v[150:153], v[194:197], v[90:93]
	v_mfma_f32_16x16x32_bf16 v[82:85], v[158:161], v[194:197], v[82:85]
	v_mfma_f32_16x16x32_bf16 v[74:77], v[150:153], v[202:205], v[74:77]
	v_mfma_f32_16x16x32_bf16 v[66:69], v[158:161], v[202:205], v[66:69]
	s_barrier
; #define PG8_STAGE(bufoff, gbase, voff) do { _Pragma("unroll") for (int _i = 0; _i < 2; ++_i) \
;         __builtin_amdgcn_global_load_lds((const unsigned*)((const char*)(gbase) + (voff)[_i]), (PG8_LAS unsigned*)(lds + (bufoff) + ldsw + _i * 8192), 16, 0, 0); } while (0)
; #define PG8_LDA(dst, b, h) do { _Pragma("unroll") for (int m = 0; m < 4; ++m) _Pragma("unroll") for (int k = 0; k < 2; ++k) dst[m][k] = *(const PG8_LAS bf16x8*)(lds + PG8_SA(b, h) + aoff + m * 2048 + k * 1024); } while (0)
; #define PG8_MMA(ai, bj, At, Bt) do { __builtin_amdgcn_s_setprio(1); _Pragma("unroll") for (int m = 0; m < 4; ++m) _Pragma("unroll") for (int n = 0; n < 2; ++n) _Pragma("unroll") for (int k = 0; k < 2; ++k) \
;         acc[ai][bj][m][n] = __builtin_amdgcn_mfma_f32_16x16x32_bf16(Bt[n][k], At[m][k], acc[ai][bj][m][n], 0, 0, 0); __builtin_amdgcn_s_setprio(0); } while (0)
; #define PG8_WAIT_V(n) asm volatile("s_waitcnt vmcnt(" #n ")" ::: "memory")
; #define PG8_WAIT_L(n) asm volatile("s_waitcnt lgkmcnt(" #n ")" ::: "memory")
; #define PG8_BAR __builtin_amdgcn_s_barrier()
; #define PG8_SCHED __builtin_amdgcn_sched_barrier(0)
; template <class Epi, class Sched, bool ALIGN_EPI = false, bool SP2 = false>
; __device__ __forceinline__ void gemm_phase(PG8_LAS unsigned char* lds, const Gemm g, const Sched& S, const Epi& E) {
;     ...
;             PG8_LDA(At, 1, 1); PG8_STAGE(PG8_SB(1, 0), b3, voffB); PG8_STAGE(PG8_SB(1, 1), b3 + hstep, voffB); PG8_STAGE(PG8_SA(1, 0), a3, voffA);
;             PG8_WAIT_V(8); PG8_WAIT_L(0); PG8_BAR; PG8_MMA(1, 0, At, B0); PG8_MMA(1, 1, At, B1); PG8_BAR; PG8_SCHED;
;     ...
;         if constexpr (ALIGN_EPI) { if (wr == 0) PG8_BAR; }
;         if constexpr (!Epi::AFTER_DRAIN) { E(acc, cur, wr, wc, fr, fq); S.done(cur); }
	s_setprio 0
	ds_read_b128 v[162:165], v230 offset:49152
	ds_read_b128 v[166:169], v230 offset:50176
	ds_read_b128 v[170:173], v230 offset:51200
	ds_read_b128 v[174:177], v230 offset:52224
	ds_read_b128 v[178:181], v230 offset:53248
	ds_read_b128 v[194:197], v230 offset:54272
	ds_read_b128 v[198:201], v230 offset:55296
	ds_read_b128 v[202:205], v230 offset:56320
	s_add_i32 s44, s64, s92
	s_mov_b32 m0, s44
	v_lshl_add_u64 v[206:207], v[206:207], 0, s[34:35]
	global_load_lds_dwordx4 v[206:207], off
	v_lshl_add_u64 v[206:207], v[208:209], 0, s[34:35]
	s_add_i32 m0, s44, 0x2000
	s_add_i32 s44, s65, s92
	global_load_lds_dwordx4 v[206:207], off
	s_mov_b32 m0, s44
	v_lshl_add_u64 v[206:207], v[210:211], 0, s[34:35]
	global_load_lds_dwordx4 v[206:207], off
	s_add_i32 m0, s44, 0x2000
	v_lshl_add_u64 v[206:207], v[232:233], 0, s[34:35]
	global_load_lds_dwordx4 v[206:207], off
	s_mov_b32 m0, s97
	v_lshl_add_u64 v[206:207], v[234:235], 0, s[34:35]
	global_load_lds_dwordx4 v[206:207], off
	s_mov_b32 m0, s98
	v_lshl_add_u64 v[206:207], v[236:237], 0, s[34:35]
	global_load_lds_dwordx4 v[206:207], off
	s_add_u32 s42, s42, 0x100
	s_addc_u32 s43, s43, 0
	s_add_u32 s17, s17, 0x100
	s_addc_u32 s60, s60, 0
	s_cmp_ge_u32 s61, s4
	s_mov_b32 s44, s61
	s_setprio 1
	s_waitcnt vmcnt(8) lgkmcnt(0)
	s_barrier
	v_mfma_f32_16x16x32_bf16 v[62:65], v[130:133], v[162:165], v[62:65]
	v_mfma_f32_16x16x32_bf16 v[54:57], v[138:141], v[162:165], v[54:57]
	v_mfma_f32_16x16x32_bf16 v[46:49], v[130:133], v[170:173], v[46:49]
	v_mfma_f32_16x16x32_bf16 v[38:41], v[138:141], v[170:173], v[38:41]
	v_mfma_f32_16x16x32_bf16 v[30:33], v[130:133], v[178:181], v[30:33]
	v_mfma_f32_16x16x32_bf16 v[22:25], v[138:141], v[178:181], v[22:25]
	v_mfma_f32_16x16x32_bf16 v[14:17], v[130:133], v[198:201], v[14:17]
	v_mfma_f32_16x16x32_bf16 v[6:9], v[138:141], v[198:201], v[6:9]
	v_mfma_f32_16x16x32_bf16 v[62:65], v[134:137], v[166:169], v[62:65]
	v_mfma_f32_16x16x32_bf16 v[54:57], v[142:145], v[166:169], v[54:57]
	v_mfma_f32_16x16x32_bf16 v[46:49], v[134:137], v[174:177], v[46:49]
	v_mfma_f32_16x16x32_bf16 v[38:41], v[142:145], v[174:177], v[38:41]
	v_mfma_f32_16x16x32_bf16 v[30:33], v[134:137], v[194:197], v[30:33]
	v_mfma_f32_16x16x32_bf16 v[22:25], v[142:145], v[194:197], v[22:25]
	v_mfma_f32_16x16x32_bf16 v[14:17], v[134:137], v[202:205], v[14:17]
	v_mfma_f32_16x16x32_bf16 v[6:9], v[142:145], v[202:205], v[6:9]
	v_mfma_f32_16x16x32_bf16 v[58:61], v[146:149], v[162:165], v[58:61]
	v_mfma_f32_16x16x32_bf16 v[50:53], v[154:157], v[162:165], v[50:53]
	v_mfma_f32_16x16x32_bf16 v[42:45], v[146:149], v[170:173], v[42:45]
	v_mfma_f32_16x16x32_bf16 v[34:37], v[154:157], v[170:173], v[34:37]
	v_mfma_f32_16x16x32_bf16 v[26:29], v[146:149], v[178:181], v[26:29]
	v_mfma_f32_16x16x32_bf16 v[18:21], v[154:157], v[178:181], v[18:21]
	v_mfma_f32_16x16x32_bf16 v[10:13], v[146:149], v[198:201], v[10:13]
	v_mfma_f32_16x16x32_bf16 v[2:5], v[154:157], v[198:201], v[2:5]
	v_mfma_f32_16x16x32_bf16 v[58:61], v[150:153], v[166:169], v[58:61]
	v_mfma_f32_16x16x32_bf16 v[50:53], v[158:161], v[166:169], v[50:53]
	v_mfma_f32_16x16x32_bf16 v[42:45], v[150:153], v[174:177], v[42:45]
	v_mfma_f32_16x16x32_bf16 v[34:37], v[158:161], v[174:177], v[34:37]
	v_mfma_f32_16x16x32_bf16 v[26:29], v[150:153], v[194:197], v[26:29]
	v_mfma_f32_16x16x32_bf16 v[18:21], v[158:161], v[194:197], v[18:21]
	v_mfma_f32_16x16x32_bf16 v[10:13], v[150:153], v[202:205], v[10:13]
	v_mfma_f32_16x16x32_bf16 v[2:5], v[158:161], v[202:205], v[2:5]
	s_barrier
	s_setprio 0
	s_cbranch_scc0 .LBB0_441
	s_and_b64 vcc, exec, s[36:37]
	s_cbranch_vccz .LBB0_445
	s_barrier
	s_cmp_lt_i32 s0, 2
	s_mov_b64 s[42:43], -1
	s_cbranch_scc0 .LBB0_446
